# attn_prompt: dropped over-conservative vmcnt waits around K/V staging and prefetch (loads are retired once per task)
# speedup vs baseline: 1.0031x; 1.0031x over previous
; #define LAS __attribute__((address_space(3)))
; __device__ __forceinline__ void attn_prompt(const Params& p, int j, LAS unsigned char* lds, const int wave, const int lane) {
;     ...
;     LAS unsigned char* Kl = lds;
;     LAS unsigned char* Vl = lds + 39424;
;     const int fr = lane & 15, g4 = lane >> 4, tid = wave * 64 + lane;
;     typedef short s16x4_ __attribute__((ext_vector_type(4)));
;     u32x4 kreg[5], vreg[5]; bf16x8 qn0, qn1;
;     ...
;     int bt = blockIdx.x;
;     if (bt < 3072) ATT_LOAD(bt);
;     for (; bt < 3072; bt += gridDim.x) {
; #pragma unroll
;         for (int i = 0; i < 5; ++i) { const int idx = tid + 512 * i; if (idx < 2176) { const int row = idx >> 3, ch = idx & 7;
;             *(LAS u32x4*)(Kl + row * 144 + ch * 16) = kreg[i];
;             *(LAS u32x2*)(Vl + row * 136 + ch * 16) = (u32x2){vreg[i].x, vreg[i].y}; *(LAS u32x2*)(Vl + row * 136 + ch * 16 + 8) = (u32x2){vreg[i].z, vreg[i].w}; } }
;         __syncthreads();
;         const bf16x8 qf0 = qn0, qf1 = qn1;
;         if (bt + (int)gridDim.x < 3072) ATT_LOAD(bt + (int)gridDim.x);
;         ATT_DECODE(bt, g, dsh, rho, b, h, q0b);
;         const int q0 = q0b + 16 * wave;
;         const bf16_t* Pb = P + (size_t)b * SEQ * OIN + g * 512 + h * 64;
;         const int tq = ((q0 + fr) << dsh) + rho;
.LBB0_289:
	s_and_b64 vcc, exec, s[36:37]
	s_cbranch_vccnz .LBB0_322
	s_movk_i32 s2, 0x880
	v_add_u32_e32 v56, 0x200, v48
	s_movk_i32 s5, 0x680
	v_add_u32_e32 v58, 0x400, v48
	v_add_u32_e32 v60, 0x600, v48
	v_add_u32_e32 v62, 0x800, v48
	v_lshlrev_b32_e32 v53, 3, v49
	s_lshl_b32 s0, s0, 4
	v_lshlrev_b32_e32 v54, 3, v50
	v_lshlrev_b32_e32 v50, 2, v50
	v_cmp_gt_i32_e64 s[38:39], s2, v48
	v_ashrrev_i32_e32 v88, 3, v48
	s_movk_i32 s2, 0x88
	v_cmp_gt_i32_e64 s[40:41], s5, v48
	v_ashrrev_i32_e32 v89, 3, v56
	s_movk_i32 s5, 0x480
	v_ashrrev_i32_e32 v90, 3, v58
	v_ashrrev_i32_e32 v91, 3, v60
	v_ashrrev_i32_e32 v92, 3, v62
	v_and_b32_e32 v52, 56, v53
	v_lshrrev_b32_e32 v55, 2, v77
	v_and_b32_e32 v78, 24, v53
	s_movk_i32 s3, 0x90
	v_mul_lo_u32 v53, v88, s2
	v_mul_lo_u32 v57, v89, s2
	v_cmp_gt_i32_e64 s[42:43], s5, v48
	v_mul_lo_u32 v59, v90, s2
	s_movk_i32 s5, 0x280
	v_mul_lo_u32 v61, v91, s2
	v_mul_lo_u32 v62, v92, s2
	v_sub_u32_e32 v63, v77, v50
	s_add_i32 s2, s0, 0xffffff70
	v_add_u32_e32 v51, 0, v184
	v_and_b32_e32 v76, 0x70, v49
	v_cmp_gt_u32_e64 s[36:37], 16, v49
	v_mul_lo_u32 v49, v88, s3
	v_mul_lo_u32 v56, v89, s3
	v_mul_lo_u32 v58, v90, s3
	v_cmp_gt_i32_e64 s[44:45], s5, v48
	v_mul_lo_u32 v60, v91, s3
	v_cmp_gt_i32_e64 s[46:47], s78, v48
	v_mul_lo_u32 v48, v92, s3
	v_add_u32_e32 v93, 0x7d, v63
	v_add_u32_e32 v94, s2, v50
	v_sub_u32_e32 v63, v50, v77
	v_or_b32_e32 v55, s0, v55
	s_mov_b32 s2, 0x9a00
	s_mov_b32 s66, s56
	v_or_b32_e32 v79, s0, v77
	s_movk_i32 s56, 0x90
	s_movk_i32 s34, 0x88
	v_add_u32_e32 v95, 0xffffff70, v63
	v_add_u32_e32 v96, v55, v50
	v_add_u32_e32 v97, v51, v49
	v_add3_u32 v98, v51, v53, s2
	v_add_u32_e32 v99, v51, v56
	v_add3_u32 v100, v51, v57, s2
	v_add_u32_e32 v101, v51, v58
	v_add3_u32 v102, v51, v59, s2
	v_add_u32_e32 v103, v51, v60
	v_add3_u32 v104, v51, v61, s2
	v_add_u32_e32 v105, v51, v48
	v_add3_u32 v106, v51, v62, s2
	v_lshlrev_b32_e32 v184, 1, v52
	v_lshlrev_b32_e32 v80, 1, v54
	v_lshlrev_b32_e32 v82, 1, v50
	s_mov_b32 s7, s71
	s_waitcnt vmcnt(0)
	s_branch .LBB0_292

; #define LAS __attribute__((address_space(3)))
; __device__ __forceinline__ void attn_prompt(const Params& p, int j, LAS unsigned char* lds, const int wave, const int lane) {
;     ...
;         for (int i = 0; i < 5; ++i) { const int idx = tid + 512 * i; if (idx < 2176) { const int row = idx >> 3, ch = idx & 7;
;             *(LAS u32x4*)(Kl + row * 144 + ch * 16) = kreg[i];
;             *(LAS u32x2*)(Vl + row * 136 + ch * 16) = (u32x2){vreg[i].x, vreg[i].y}; *(LAS u32x2*)(Vl + row * 136 + ch * 16 + 8) = (u32x2){vreg[i].z, vreg[i].w}; } }
.LBB0_297:
	ds_write_b128 v105, v[32:35]
	ds_write2_b64 v106, v[36:37], v[38:39] offset1:1

.LBB0_304:
	v_add_u32_e32 v32, s30, v92
	v_max_i32_e32 v32, 0, v32
	v_lshlrev_b32_e32 v32, s17, v32
	v_add_u32_e32 v32, s26, v32
	s_movk_i32 s30, 0x2800
	v_mad_u64_u32 v[32:33], s[30:31], v32, s30, v[48:49]
	v_add_co_u32_e32 v36, vcc, 0x1000, v32
	s_nop 1
	v_addc_co_u32_e32 v37, vcc, 0, v33, vcc
	global_load_dwordx4 v[32:35], v[32:33], off offset:3072
	s_nop 0
	global_load_dwordx4 v[36:39], v[36:37], off offset:2048

; #define LAS __attribute__((address_space(3)))
; __device__ __forceinline__ void attn_prompt(const Params& p, int j, LAS unsigned char* lds, const int wave, const int lane) {
;     ...
;         for (int i = 0; i < 5; ++i) { const int idx = tid + 512 * i; if (idx < 2176) { const int row = idx >> 3, ch = idx & 7;
;             *(LAS u32x4*)(Kl + row * 144 + ch * 16) = kreg[i];
;             *(LAS u32x2*)(Vl + row * 136 + ch * 16) = (u32x2){vreg[i].x, vreg[i].y}; *(LAS u32x2*)(Vl + row * 136 + ch * 16 + 8) = (u32x2){vreg[i].z, vreg[i].w}; } }
.LBB0_306:
	ds_write_b128 v97, v[0:3]
	ds_write2_b64 v98, v[4:5], v[6:7] offset1:1
	s_or_b64 exec, exec, s[2:3]
	s_and_saveexec_b64 s[2:3], s[40:41]
	s_cbranch_execz .LBB0_294
.LBB0_307:
	ds_write_b128 v99, v[8:11]
	ds_write2_b64 v100, v[12:13], v[14:15] offset1:1
	s_or_b64 exec, exec, s[2:3]
	s_and_saveexec_b64 s[2:3], s[42:43]
	s_cbranch_execz .LBB0_295
.LBB0_308:
	ds_write_b128 v101, v[16:19]
	ds_write2_b64 v102, v[20:21], v[22:23] offset1:1
	s_or_b64 exec, exec, s[2:3]
	s_and_saveexec_b64 s[2:3], s[44:45]
	s_cbranch_execz .LBB0_296
.LBB0_309:
	ds_write_b128 v103, v[24:27]
	ds_write2_b64 v104, v[28:29], v[30:31] offset1:1
	s_or_b64 exec, exec, s[2:3]
	s_and_saveexec_b64 s[2:3], s[46:47]
	s_cbranch_execnz .LBB0_297
	s_branch .LBB0_298

; #define LAS __attribute__((address_space(3)))
; __device__ __forceinline__ void attn_prompt(const Params& p, int j, LAS unsigned char* lds, const int wave, const int lane) {
;     ...
;         for (int kp = kp0; kp < 5; ++kp) {
;             const int kbase = q0 - 144 + 32 * kp, lrow = 16 * wave + 32 * kp;
;             f32x4 st[2];
; #pragma unroll
;             for (int tl = 0; tl < 2; ++tl) {
;                 const LAS unsigned char* kr = Kl + (lrow + tl * 16 + fr) * 144 + g4 * 16;
;                 const bf16x8 kf0 = *(const LAS bf16x8*)kr, kf1 = *(const LAS bf16x8*)(kr + 64);
;                 f32x4 sv = (f32x4){0.f, 0.f, 0.f, 0.f};
;                 sv = __builtin_amdgcn_mfma_f32_16x16x32_bf16(kf0, qf0, sv, 0, 0, 0);
;                 sv = __builtin_amdgcn_mfma_f32_16x16x32_bf16(kf1, qf1, sv, 0, 0, 0);
;                 st[tl] = sv;
;             }
;             float mx = -1e30f; bool val[2][4];
; #pragma unroll
;             for (int tl = 0; tl < 2; ++tl)
; #pragma unroll
;                 for (int e = 0; e < 4; ++e) { const int uk = kbase + tl * 16 + g4 * 4 + e, dist = uq - uk; val[tl][e] = (uk >= 0) && (dist >= 0) && (dist <= 128);
;                     st[tl][e] = val[tl][e] ? st[tl][e] * 0.125f : -1e30f; mx = fmaxf(mx, st[tl][e]); }
;             mx = xmax4(mx);
;             const float mnew = fmaxf(mrun, mx), sc = __expf(mrun - mnew);
;             mrun = mnew; lrun *= sc;
; #pragma unroll
;             for (int dt = 0; dt < 4; ++dt) acc[dt] = acc[dt] * sc;
;             float pv[2][4];
; #pragma unroll
;             for (int tl = 0; tl < 2; ++tl)
; #pragma unroll
;                 for (int e = 0; e < 4; ++e) { pv[tl][e] = val[tl][e] ? __expf(st[tl][e] - mnew) : 0.f; lrun += pv[tl][e]; }
;             bf16x8 pf;
;             { u32x4 w; w.x = pk2(pv[0][0], pv[0][1]); w.y = pk2(pv[0][2], pv[0][3]); w.z = pk2(pv[1][0], pv[1][1]); w.w = pk2(pv[1][2], pv[1][3]); pf = __builtin_bit_cast(bf16x8, w); }
; #pragma unroll
;             for (int dt = 0; dt < 4; ++dt) {
;                 LAS unsigned char* ta = Vl + (lrow + g4 * 4 + (fr >> 2)) * 136 + dt * 32 + 8 * (fr & 3);
;                 const s16x4_ lo = __builtin_amdgcn_ds_read_tr16_b64_v4i16((LAS s16x4_*)ta), hi = __builtin_amdgcn_ds_read_tr16_b64_v4i16((LAS s16x4_*)(ta + 2176));
;                 const bf16x8 vf = (bf16x8){lo[0], lo[1], lo[2], lo[3], hi[0], hi[1], hi[2], hi[3]};
.LBB0_313:
	v_add_u32_e32 v74, 0, v84
	ds_read_b128 v[108:111], v74
	ds_read_b128 v[112:115], v74 offset:64
	v_mov_b32_e32 v73, v85
	v_add_u32_e32 v85, 17, v81
	v_cmp_lt_i32_e64 s[52:53], -1, v83
	s_waitcnt lgkmcnt(1)
	v_mfma_f32_16x16x32_bf16 v[108:111], v[108:111], v[40:43], 0
	v_cmp_gt_u32_e64 s[50:51], s35, v85
	s_and_b64 s[50:51], s[52:53], s[50:51]
	s_movk_i32 s26, 0xff7e
	s_waitcnt lgkmcnt(0)
	v_mfma_f32_16x16x32_bf16 v[108:111], v[112:115], v[44:47], v[108:111]
	ds_read_b128 v[112:115], v74 offset:2304
	ds_read_b128 v[116:119], v74 offset:2368
	v_add_u32_e32 v74, 19, v81
	v_cmp_gt_u32_e32 vcc, s35, v74
	s_waitcnt lgkmcnt(1)
	v_mfma_f32_16x16x32_bf16 v[112:115], v[112:115], v[40:43], 0
	s_nop 1
	v_mul_f32_e32 v85, 0x3e000000, v110
	v_mul_f32_e32 v74, 0x3e000000, v108
	v_cndmask_b32_e64 v108, v221, v85, s[50:51]
	v_add_u32_e32 v85, 16, v81
	v_cmp_lt_u32_e64 s[48:49], s26, v107
	v_cmp_gt_u32_e64 s[54:55], s35, v85
	s_waitcnt lgkmcnt(0)
	v_mfma_f32_16x16x32_bf16 v[112:115], v[116:119], v[44:47], v[112:115]
	s_and_b64 vcc, s[52:53], vcc
	s_and_b64 s[48:49], s[52:53], s[48:49]
	s_and_b64 s[52:53], s[52:53], s[54:55]
	v_mul_f32_e32 v85, 0x3e000000, v111
	v_cndmask_b32_e32 v75, v221, v74, vcc
	v_mul_f32_e32 v74, 0x3e000000, v109
	v_cndmask_b32_e64 v109, v221, v85, s[52:53]
	v_add_u32_e32 v85, 16, v83
	v_cmp_lt_i32_e64 s[58:59], -1, v85
	v_add_u32_e32 v85, 3, v81
	v_cmp_gt_u32_e64 s[54:55], s35, v85
	s_and_b64 s[54:55], s[58:59], s[54:55]
	v_mul_f32_e32 v85, 0x3e000000, v112
	v_cndmask_b32_e64 v110, v221, v85, s[54:55]
	v_add_u32_e32 v85, 2, v81
	v_cmp_gt_u32_e64 s[60:61], s35, v85
	s_and_b64 s[60:61], s[58:59], s[60:61]
	v_mul_f32_e32 v85, 0x3e000000, v113
	v_cndmask_b32_e64 v111, v221, v85, s[60:61]
	v_add_u32_e32 v85, 1, v81
	v_cndmask_b32_e64 v87, v221, v74, s[48:49]
	s_mov_b32 s26, 0xf149f2ca
	v_cmp_gt_u32_e64 s[62:63], s35, v85
	v_max3_f32 v74, v75, s26, v87
	s_and_b64 s[62:63], s[58:59], s[62:63]
	v_mul_f32_e32 v85, 0x3e000000, v114
	v_cmp_gt_u32_e64 s[64:65], s35, v81
	v_max3_f32 v74, v74, v108, v109
	v_cndmask_b32_e64 v112, v221, v85, s[62:63]
	s_and_b64 s[58:59], s[58:59], s[64:65]
	v_mul_f32_e32 v85, 0x3e000000, v115
	v_max3_f32 v74, v74, v110, v111
	v_cndmask_b32_e64 v113, v221, v85, s[58:59]
	v_max3_f32 v74, v74, v112, v113
	v_mov_b32_e32 v85, v74
	s_nop 1
	v_permlane16_swap_b32 v74, v85
	s_add_i32 s25, s25, 1
	v_max_f32_e32 v85, v85, v85
	v_max_f32_e32 v74, v74, v74
	v_max_f32_e32 v74, v74, v85
	v_mov_b32_e32 v85, v74
	s_nop 1
	v_permlane32_swap_b32 v74, v85
	v_subrev_u32_e32 v81, 32, v81
	v_max3_f32 v85, v73, v74, v85
	v_sub_f32_e32 v73, v73, v85
	v_mul_f32_e32 v73, 0x3fb8aa3b, v73
	v_exp_f32_e32 v74, v73
	v_sub_f32_e32 v73, v75, v85
	v_mul_f32_e32 v73, 0x3fb8aa3b, v73
	v_exp_f32_e32 v73, v73
	v_pk_mul_f32 v[70:71], v[70:71], v[74:75] op_sel_hi:[1,0]
	v_pk_mul_f32 v[68:69], v[68:69], v[74:75] op_sel_hi:[1,0]
	v_pk_mul_f32 v[66:67], v[66:67], v[74:75] op_sel_hi:[1,0]
	v_cndmask_b32_e32 v73, 0, v73, vcc
	v_pk_mul_f32 v[64:65], v[64:65], v[74:75] op_sel_hi:[1,0]
	v_pk_mul_f32 v[62:63], v[62:63], v[74:75] op_sel_hi:[1,0]
	v_pk_mul_f32 v[60:61], v[60:61], v[74:75] op_sel_hi:[1,0]
	v_pk_mul_f32 v[58:59], v[58:59], v[74:75] op_sel_hi:[1,0]
	v_pk_mul_f32 v[56:57], v[56:57], v[74:75] op_sel_hi:[1,0]
	v_fma_f32 v72, v72, v74, v73
	v_sub_f32_e32 v74, v87, v85
	v_mul_f32_e32 v74, 0x3fb8aa3b, v74
	v_sub_f32_e32 v75, v108, v85
	v_exp_f32_e32 v74, v74
	v_mul_f32_e32 v75, 0x3fb8aa3b, v75
	v_sub_f32_e32 v87, v109, v85
	v_exp_f32_e32 v75, v75
	v_mul_f32_e32 v87, 0x3fb8aa3b, v87
	v_sub_f32_e32 v108, v110, v85
	v_exp_f32_e32 v87, v87
	v_mul_f32_e32 v108, 0x3fb8aa3b, v108
	v_sub_f32_e32 v109, v111, v85
	v_exp_f32_e32 v108, v108
	v_mul_f32_e32 v109, 0x3fb8aa3b, v109
	v_sub_f32_e32 v110, v112, v85
	v_cndmask_b32_e64 v74, 0, v74, s[48:49]
	v_exp_f32_e32 v109, v109
	v_mul_f32_e32 v110, 0x3fb8aa3b, v110
	v_add_f32_e32 v72, v74, v72
	v_cndmask_b32_e64 v75, 0, v75, s[50:51]
	v_exp_f32_e32 v110, v110
	v_add_f32_e32 v72, v75, v72
	v_cndmask_b32_e64 v87, 0, v87, s[52:53]
	v_add_f32_e32 v72, v87, v72
	v_cndmask_b32_e64 v108, 0, v108, s[54:55]
	v_add_f32_e32 v72, v108, v72
	v_cndmask_b32_e64 v109, 0, v109, s[60:61]
	v_add_f32_e32 v72, v109, v72
	v_cndmask_b32_e64 v110, 0, v110, s[62:63]
	v_add_f32_e32 v116, v110, v72
	v_sub_f32_e32 v72, v113, v85
	v_mul_f32_e32 v72, 0x3fb8aa3b, v72
	v_exp_f32_e32 v72, v72
	v_add_u32_e32 v83, 32, v83
	v_add_u32_e32 v107, 32, v107
	v_add_u32_e32 v84, 0x1200, v84
	v_cndmask_b32_e64 v117, 0, v72, s[58:59]
	v_bfe_u32 v72, v73, 16, 1
	v_add3_u32 v72, v73, v72, s6
	v_bfe_u32 v73, v74, 16, 1
	v_lshrrev_b32_e32 v72, 16, v72
	v_add3_u32 v73, v74, v73, s6
	v_and_or_b32 v72, v73, s27, v72
	v_bfe_u32 v73, v75, 16, 1
	v_add3_u32 v73, v75, v73, s6
	v_bfe_u32 v74, v87, 16, 1
	v_lshrrev_b32_e32 v73, 16, v73
	v_add3_u32 v74, v87, v74, s6
	v_and_or_b32 v73, v74, s27, v73
	v_bfe_u32 v74, v108, 16, 1
	v_add3_u32 v74, v108, v74, s6
	v_bfe_u32 v75, v109, 16, 1
	v_lshrrev_b32_e32 v74, 16, v74
	v_add3_u32 v75, v109, v75, s6
	v_and_or_b32 v74, v75, s27, v74
	v_bfe_u32 v75, v110, 16, 1
	v_add3_u32 v75, v110, v75, s6
	v_bfe_u32 v87, v117, 16, 1
	v_lshrrev_b32_e32 v75, 16, v75
	v_add3_u32 v87, v117, v87, s6
	v_and_or_b32 v75, v87, s27, v75
	v_add_u32_e32 v87, 0, v86
	ds_read_b64_tr_b16 v[110:111], v87 offset:41600
	ds_read_b64_tr_b16 v[108:109], v87 offset:39424
	ds_read_b64_tr_b16 v[112:113], v87 offset:39456
	s_waitcnt lgkmcnt(1)
	v_mfma_f32_16x16x32_bf16 v[68:71], v[108:111], v[72:75], v[68:71]
	ds_read_b64_tr_b16 v[114:115], v87 offset:41632
	ds_read_b64_tr_b16 v[108:109], v87 offset:39488
	ds_read_b64_tr_b16 v[110:111], v87 offset:41664
	v_add_u32_e32 v86, 0x1100, v86
	s_waitcnt lgkmcnt(0)
	v_mfma_f32_16x16x32_bf16 v[60:63], v[108:111], v[72:75], v[60:63]
	ds_read_b64_tr_b16 v[108:109], v87 offset:39520
	ds_read_b64_tr_b16 v[110:111], v87 offset:41696
	s_cmp_gt_u32 s25, 3
	v_mfma_f32_16x16x32_bf16 v[64:67], v[112:115], v[72:75], v[64:67]
	s_waitcnt lgkmcnt(0)
	v_mfma_f32_16x16x32_bf16 v[56:59], v[108:111], v[72:75], v[56:59]
	v_add_f32_e32 v72, v117, v116
	s_cbranch_scc0 .LBB0_313
	s_branch .LBB0_315

; __device__ __forceinline__ unsigned pk2(float lo, float hi) { return f2bf(lo) | (f2bf(hi) << 16); }
; __device__ __forceinline__ void attn_prompt(const Params& p, int j, LAS unsigned char* lds, const int wave, const int lane) {
;     ...
;         lrun = xsum4(lrun);
;         const float inv = 1.f / lrun;
;         const size_t n = (size_t)b * SEQ + tq;
;         bf16_t* og = OG + ((size_t)g * NP + n) * 512 + h * 64 + g4 * 4;
; #pragma unroll
;         for (int dt = 0; dt < 4; ++dt) { u32x2 w; w.x = pk2(acc[dt][0] * inv, acc[dt][1] * inv); w.y = pk2(acc[dt][2] * inv, acc[dt][3] * inv); *(u32x2*)(og + dt * 16) = w; }
;         if (g4 == 0) LSE[((size_t)g * NP + n) * 8 + h] = mrun + __logf(lrun);
.LBB0_315:
	v_mov_b32_e32 v41, v72
	s_nop 1
	v_permlane16_swap_b32 v72, v41
	s_lshl_b32 s25, s13, 4
	v_add_f32_e32 v41, v72, v41
	v_mov_b32_e32 v42, v41
	s_nop 1
	v_permlane32_swap_b32 v41, v42
	s_and_b32 s30, s25, 0x3800
	v_add_f32_e32 v42, v41, v42
	v_or_b32_e32 v40, s24, v77
	v_div_scale_f32 v41, s[24:25], v42, v42, 1.0
	v_rcp_f32_e32 v43, v41
	s_sub_i32 s26, 4, s17
	s_lshl_b32 s27, -1, s17
	s_lshr_b32 s13, s13, s26
	v_fma_f32 v44, -v41, v43, 1.0
	v_fmac_f32_e32 v43, v44, v43
	v_div_scale_f32 v44, vcc, 1.0, v42, 1.0
	v_mul_f32_e32 v45, v44, v43
	v_fma_f32 v46, -v41, v45, v44
	v_lshlrev_b32_e32 v40, s17, v40
	s_andn2_b32 s13, s13, s27
	v_fmac_f32_e32 v45, v46, v43
	v_add_u32_e32 v40, s13, v40
	v_fma_f32 v41, -v41, v45, v44
	s_ashr_i32 s13, s12, 31
	v_div_fmas_f32 v41, v41, v43, v45
	s_lshl_b64 s[12:13], s[12:13], 14
	v_div_fixup_f32 v44, v41, v42, 1.0
	v_ashrrev_i32_e32 v41, 31, v40
	s_or_b32 s12, s12, s30
	v_mov_b32_e32 v73, v70
	v_mov_b32_e32 v70, v69
	v_lshl_add_u64 v[40:41], s[12:13], 0, v[40:41]
	v_readlane_b32 s12, v253, 14
	v_mov_b32_e32 v72, v68
	v_pk_mul_f32 v[68:69], v[70:71], v[44:45] op_sel_hi:[1,0]
	s_bfe_u32 s7, s7, 0x30004
	v_lshlrev_b64 v[46:47], 10, v[40:41]
	v_readlane_b32 s13, v253, 15
	v_pk_mul_f32 v[72:73], v[72:73], v[44:45] op_sel_hi:[1,0]
	v_and_b32_sdwa v70, v69, v197 dst_sel:DWORD dst_unused:UNUSED_PAD src0_sel:WORD_1 src1_sel:DWORD
	v_and_b32_sdwa v71, v68, v197 dst_sel:DWORD dst_unused:UNUSED_PAD src0_sel:WORD_1 src1_sel:DWORD
	v_lshl_add_u64 v[46:47], s[12:13], 0, v[46:47]
	s_lshl_b32 s96, s7, 7
	v_and_b32_sdwa v43, v73, v197 dst_sel:DWORD dst_unused:UNUSED_PAD src0_sel:WORD_1 src1_sel:DWORD
	v_and_b32_sdwa v45, v72, v197 dst_sel:DWORD dst_unused:UNUSED_PAD src0_sel:WORD_1 src1_sel:DWORD
	v_add3_u32 v69, v69, v70, s6
	v_add3_u32 v68, v68, v71, s6
	v_lshl_add_u64 v[46:47], v[46:47], 0, s[96:97]
	v_mov_b32_e32 v83, v185
	v_add3_u32 v45, v72, v45, s6
	v_add3_u32 v43, v73, v43, s6
	v_and_b32_e32 v69, 0xffff0000, v69
	v_and_b32_e32 v68, 0xffff0000, v68
	v_lshl_add_u64 v[46:47], v[46:47], 0, v[82:83]
	v_or_b32_sdwa v69, v69, v43 dst_sel:DWORD dst_unused:UNUSED_PAD src0_sel:DWORD src1_sel:WORD_1
	v_or_b32_sdwa v68, v68, v45 dst_sel:DWORD dst_unused:UNUSED_PAD src0_sel:DWORD src1_sel:WORD_1
	global_store_dwordx2 v[46:47], v[68:69], off
	v_mov_b32_e32 v69, v66
	v_mov_b32_e32 v66, v65
	v_mov_b32_e32 v68, v64
	v_pk_mul_f32 v[64:65], v[66:67], v[44:45] op_sel_hi:[1,0]
	v_pk_mul_f32 v[68:69], v[68:69], v[44:45] op_sel_hi:[1,0]
	v_and_b32_sdwa v66, v65, v197 dst_sel:DWORD dst_unused:UNUSED_PAD src0_sel:WORD_1 src1_sel:DWORD
	v_and_b32_sdwa v67, v64, v197 dst_sel:DWORD dst_unused:UNUSED_PAD src0_sel:WORD_1 src1_sel:DWORD
	v_and_b32_sdwa v43, v69, v197 dst_sel:DWORD dst_unused:UNUSED_PAD src0_sel:WORD_1 src1_sel:DWORD
	v_and_b32_sdwa v45, v68, v197 dst_sel:DWORD dst_unused:UNUSED_PAD src0_sel:WORD_1 src1_sel:DWORD
	v_add3_u32 v65, v65, v66, s6
	v_add3_u32 v64, v64, v67, s6
	v_add3_u32 v45, v68, v45, s6
	v_add3_u32 v43, v69, v43, s6
	v_and_b32_e32 v65, 0xffff0000, v65
	v_and_b32_e32 v64, 0xffff0000, v64
	v_or_b32_sdwa v65, v65, v43 dst_sel:DWORD dst_unused:UNUSED_PAD src0_sel:DWORD src1_sel:WORD_1
	v_or_b32_sdwa v64, v64, v45 dst_sel:DWORD dst_unused:UNUSED_PAD src0_sel:DWORD src1_sel:WORD_1
	global_store_dwordx2 v[46:47], v[64:65], off offset:32
	v_mov_b32_e32 v65, v62
	v_mov_b32_e32 v62, v61
	v_mov_b32_e32 v64, v60
	v_pk_mul_f32 v[60:61], v[62:63], v[44:45] op_sel_hi:[1,0]
	v_pk_mul_f32 v[64:65], v[64:65], v[44:45] op_sel_hi:[1,0]
	v_and_b32_sdwa v62, v61, v197 dst_sel:DWORD dst_unused:UNUSED_PAD src0_sel:WORD_1 src1_sel:DWORD
	v_and_b32_sdwa v63, v60, v197 dst_sel:DWORD dst_unused:UNUSED_PAD src0_sel:WORD_1 src1_sel:DWORD
	v_and_b32_sdwa v43, v65, v197 dst_sel:DWORD dst_unused:UNUSED_PAD src0_sel:WORD_1 src1_sel:DWORD
	v_and_b32_sdwa v45, v64, v197 dst_sel:DWORD dst_unused:UNUSED_PAD src0_sel:WORD_1 src1_sel:DWORD
	v_add3_u32 v61, v61, v62, s6
	v_add3_u32 v60, v60, v63, s6
	v_add3_u32 v45, v64, v45, s6
	v_add3_u32 v43, v65, v43, s6
	v_and_b32_e32 v61, 0xffff0000, v61
	v_and_b32_e32 v60, 0xffff0000, v60
	v_or_b32_sdwa v61, v61, v43 dst_sel:DWORD dst_unused:UNUSED_PAD src0_sel:DWORD src1_sel:WORD_1
	v_or_b32_sdwa v60, v60, v45 dst_sel:DWORD dst_unused:UNUSED_PAD src0_sel:DWORD src1_sel:WORD_1
	global_store_dwordx2 v[46:47], v[60:61], off offset:64
	v_mov_b32_e32 v60, v56
	v_mov_b32_e32 v61, v58
	v_mov_b32_e32 v58, v57
	v_pk_mul_f32 v[60:61], v[60:61], v[44:45] op_sel_hi:[1,0]
	v_pk_mul_f32 v[44:45], v[58:59], v[44:45] op_sel_hi:[1,0]
	v_and_b32_sdwa v43, v61, v197 dst_sel:DWORD dst_unused:UNUSED_PAD src0_sel:WORD_1 src1_sel:DWORD
	v_and_b32_sdwa v57, v45, v197 dst_sel:DWORD dst_unused:UNUSED_PAD src0_sel:WORD_1 src1_sel:DWORD
	v_and_b32_sdwa v58, v44, v197 dst_sel:DWORD dst_unused:UNUSED_PAD src0_sel:WORD_1 src1_sel:DWORD
	v_and_b32_sdwa v56, v60, v197 dst_sel:DWORD dst_unused:UNUSED_PAD src0_sel:WORD_1 src1_sel:DWORD
	v_add3_u32 v45, v45, v57, s6
	v_add3_u32 v44, v44, v58, s6
	v_add3_u32 v56, v60, v56, s6
	v_add3_u32 v43, v61, v43, s6
	v_and_b32_e32 v45, 0xffff0000, v45
	v_and_b32_e32 v44, 0xffff0000, v44
	v_or_b32_sdwa v45, v45, v43 dst_sel:DWORD dst_unused:UNUSED_PAD src0_sel:DWORD src1_sel:WORD_1
	v_or_b32_sdwa v44, v44, v56 dst_sel:DWORD dst_unused:UNUSED_PAD src0_sel:DWORD src1_sel:WORD_1
	global_store_dwordx2 v[46:47], v[44:45], off offset:96
	s_and_saveexec_b64 s[12:13], s[36:37]
	s_cbranch_execz .LBB0_291
	v_cmp_gt_f32_e32 vcc, s15, v42
	s_mov_b32 s17, 0x3f317217
	v_readlane_b32 s24, v253, 16
	v_cndmask_b32_e64 v43, 0, 32, vcc
	v_ldexp_f32 v42, v42, v43
	v_log_f32_e32 v42, v42
	v_cndmask_b32_e32 v43, 0, v222, vcc
	v_lshlrev_b64 v[40:41], 5, v[40:41]
	v_readlane_b32 s25, v253, 17
	v_mul_f32_e32 v44, 0x3f317217, v42
	v_fma_f32 v44, v42, s17, -v44
	v_fmac_f32_e32 v44, 0x3377d1cf, v42
	s_mov_b32 s17, 0x7f800000
	v_fmac_f32_e32 v44, 0x3f317217, v42
	v_cmp_lt_f32_e64 vcc, |v42|, s17
	v_lshl_add_u64 v[40:41], s[24:25], 0, v[40:41]
	s_lshl_b32 s96, s7, 2
	v_cndmask_b32_e32 v42, v42, v44, vcc
	v_sub_f32_e32 v42, v42, v43
	v_add_f32_e32 v42, v85, v42
	v_lshl_add_u64 v[40:41], v[40:41], 0, s[96:97]
	global_store_dword v[40:41], v42, off
	s_branch .LBB0_291
.LBB0_317:
	v_add_u32_e32 v0, s30, v88
	v_max_i32_e32 v0, 0, v0
	v_lshlrev_b32_e32 v0, s17, v0
	v_add_u32_e32 v0, s26, v0
	s_movk_i32 s31, 0x2800
	v_mad_u64_u32 v[0:1], s[48:49], v0, s31, v[48:49]
	v_add_co_u32_e32 v4, vcc, 0x1000, v0
	s_nop 1
	v_addc_co_u32_e32 v5, vcc, 0, v1, vcc
	global_load_dwordx4 v[0:3], v[0:1], off offset:3072
	s_nop 0
	global_load_dwordx4 v[4:7], v[4:5], off offset:2048
	s_or_b64 exec, exec, s[24:25]
	s_and_saveexec_b64 s[24:25], s[40:41]
	s_cbranch_execz .LBB0_301
.LBB0_318:
	v_add_u32_e32 v8, s30, v89
	v_max_i32_e32 v8, 0, v8
	v_lshlrev_b32_e32 v8, s17, v8
	v_add_u32_e32 v8, s26, v8
	s_movk_i32 s31, 0x2800
	v_mad_u64_u32 v[8:9], s[48:49], v8, s31, v[48:49]
	v_add_co_u32_e32 v12, vcc, 0x1000, v8
	s_nop 1
	v_addc_co_u32_e32 v13, vcc, 0, v9, vcc
	global_load_dwordx4 v[8:11], v[8:9], off offset:3072
	s_nop 0
	global_load_dwordx4 v[12:15], v[12:13], off offset:2048
	s_or_b64 exec, exec, s[24:25]
	s_and_saveexec_b64 s[24:25], s[42:43]
	s_cbranch_execz .LBB0_302
.LBB0_319:
	v_add_u32_e32 v16, s30, v90
	v_max_i32_e32 v16, 0, v16
	v_lshlrev_b32_e32 v16, s17, v16
	v_add_u32_e32 v16, s26, v16
	s_movk_i32 s31, 0x2800
	v_mad_u64_u32 v[16:17], s[48:49], v16, s31, v[48:49]
	v_add_co_u32_e32 v20, vcc, 0x1000, v16
	s_nop 1
	v_addc_co_u32_e32 v21, vcc, 0, v17, vcc
	global_load_dwordx4 v[16:19], v[16:17], off offset:3072
	s_nop 0
	global_load_dwordx4 v[20:23], v[20:21], off offset:2048
	s_or_b64 exec, exec, s[24:25]
	s_and_saveexec_b64 s[24:25], s[44:45]
	s_cbranch_execz .LBB0_303
.LBB0_320:
	v_add_u32_e32 v24, s30, v91
	v_max_i32_e32 v24, 0, v24
	v_lshlrev_b32_e32 v24, s17, v24
	v_add_u32_e32 v24, s26, v24
	s_movk_i32 s31, 0x2800
	v_mad_u64_u32 v[24:25], s[48:49], v24, s31, v[48:49]
	v_add_co_u32_e32 v28, vcc, 0x1000, v24
	s_nop 1
	v_addc_co_u32_e32 v29, vcc, 0, v25, vcc
	global_load_dwordx4 v[24:27], v[24:25], off offset:3072
	s_nop 0
	global_load_dwordx4 v[28:31], v[28:29], off offset:2048
	s_or_b64 exec, exec, s[24:25]
	s_and_saveexec_b64 s[24:25], s[46:47]
	s_cbranch_execnz .LBB0_304
	s_branch .LBB0_305
